# attention: V/ctx-V/bias staging loads batched (one round trip) instead of load-wait-write per 64 keys
# baseline (speedup 1.0000x reference)
.LBB0_709:
	s_bfe_u32 s10, s31, 0x30002
	s_lshl_b32 s1, s10, 2
	s_add_i32 s1, s18, s1
	v_med3_i32 v0, s1, 4, 28
	s_cmpk_gt_i32 s19, 0x1ff
	v_readfirstlane_b32 s1, v0
	s_mov_b64 s[2:3], -1
	s_waitcnt vmcnt(0)
	s_barrier
	s_cbranch_scc0 .LBB0_732
	s_add_i32 s2, s19, 0xfffffe00
	s_lshr_b32 s14, s2, 7
	s_lshl_b32 s2, s19, 2
	s_and_b32 s11, s2, 28
	s_lshl_b32 s8, s14, 11
	s_add_i32 s2, s11, s18
	s_addk_i32 s8, 0x2000
	v_med3_i32 v4, s2, 4, 28
	s_lshl_b32 s2, s2, 6
	s_add_i32 s2, s8, s2
	v_or_b32_e32 v163, s2, v164
	v_mov_b64_e32 v[2:3], s[4:5]
	s_bfe_u32 s9, s19, 0x40003
	v_mad_i64_i32 v[2:3], s[2:3], v163, s29, v[2:3]
	s_lshl_b32 s20, s9, 6
	s_lshl_b32 s16, s9, 7
	s_add_i32 s2, s11, -4
	s_cmp_lg_u32 s11, 0
	s_mul_i32 s9, s8, 0x7c00
	v_med3_u32 v0, s11, 1, 25
	s_cselect_b32 s11, s2, 0
	s_mul_hi_u32 s3, s8, 0x7c00
	s_add_u32 s9, s4, s9
	v_readfirstlane_b32 s2, v4
	s_addc_u32 s3, s5, s3
	s_mul_i32 s2, s2, 0xf8000
	s_add_u32 s9, s9, s16
	v_lshl_add_u64 v[2:3], v[2:3], 0, s[16:17]
	s_addc_u32 s15, s3, 0
	s_add_i32 s16, s2, 0xffc20000
	s_lshl_b64 s[2:3], s[16:17], 1
	s_add_u32 s2, s9, s2
	v_lshl_add_u64 v[2:3], v[148:149], 1, v[2:3]
	s_addc_u32 s3, s15, s3
	global_load_dwordx4 v[66:69], v[2:3], off
	global_load_dwordx4 v[70:73], v[2:3], off offset:32
	global_load_dwordx4 v[74:77], v[2:3], off offset:64
	global_load_dwordx4 v[78:81], v[2:3], off offset:96
	v_lshl_add_u64 v[2:3], s[2:3], 0, v[150:151]
	v_lshl_add_u64 v[2:3], v[152:153], 1, v[2:3]
	global_load_dwordx4 v[82:85], v[2:3], off offset:2048
	global_load_dwordx4 v[86:89], v[2:3], off offset:2080
	global_load_dwordx4 v[90:93], v[2:3], off offset:2112
	global_load_dwordx4 v[94:97], v[2:3], off offset:2144
	v_add_co_u32_e32 v2, vcc, 0xf8000, v2
	v_subrev_u32_e32 v0, s11, v0
	s_nop 0
	v_addc_co_u32_e32 v3, vcc, 0, v3, vcc
	global_load_dwordx4 v[98:101], v[2:3], off offset:2048
	global_load_dwordx4 v[102:105], v[2:3], off offset:2080
	global_load_dwordx4 v[106:109], v[2:3], off offset:2112
	global_load_dwordx4 v[110:113], v[2:3], off offset:2144
	v_lshlrev_b32_e32 v0, 9, v0
	v_add_u32_e32 v2, 0xe00, v0
	s_lshl_b32 s15, s11, 6
	s_add_i32 s15, s15, s8
	v_readfirstlane_b32 s32, v2
	v_ashrrev_i32_e32 v8, 3, v146
	v_mov_b64_e32 v[4:5], s[4:5]
	v_add_u32_e32 v6, s15, v8
	s_lshl_b32 s16, s20, 1
	v_mad_i64_i32 v[4:5], s[24:25], v6, s29, v[4:5]
	v_lshlrev_b32_e32 v0, 1, v156
	v_lshl_add_u64 v[4:5], v[4:5], 0, s[16:17]
	v_lshl_add_u64 v[4:5], v[4:5], 0, v[0:1]
	v_add_co_u32_e32 v4, vcc, 0x1000, v4
	s_mov_b64 s[8:9], 0x1f0000
	s_nop 0
	v_addc_co_u32_e32 v5, vcc, 0, v5, vcc
	global_load_dwordx4 v[180:183], v[4:5], off
	v_lshl_add_u64 v[4:5], v[4:5], 0, s[8:9]
	global_load_dwordx4 v[184:187], v[4:5], off
	v_lshl_add_u64 v[4:5], v[4:5], 0, s[8:9]
	global_load_dwordx4 v[188:191], v[4:5], off
	v_lshl_add_u64 v[4:5], v[4:5], 0, s[8:9]
	global_load_dwordx4 v[192:195], v[4:5], off
	v_lshl_add_u64 v[4:5], v[4:5], 0, s[8:9]
	global_load_dwordx4 v[196:199], v[4:5], off
	v_lshl_add_u64 v[4:5], v[4:5], 0, s[8:9]
	global_load_dwordx4 v[200:203], v[4:5], off
	v_lshl_add_u64 v[4:5], v[4:5], 0, s[8:9]
	global_load_dwordx4 v[204:207], v[4:5], off
	v_lshl_add_u64 v[4:5], v[4:5], 0, s[8:9]
	global_load_dwordx4 v[208:211], v[4:5], off
	s_cmpk_lt_u32 s32, 0x1200
	s_cbranch_scc1 .Latt_lat_v_issued
	v_lshl_add_u64 v[4:5], v[4:5], 0, s[8:9]
	global_load_dwordx4 v[212:215], v[4:5], off
	s_cmpk_lt_u32 s32, 0x1400
	s_cbranch_scc1 .Latt_lat_v_issued
	v_lshl_add_u64 v[4:5], v[4:5], 0, s[8:9]
	global_load_dwordx4 v[216:219], v[4:5], off
	s_cmpk_lt_u32 s32, 0x1600
	s_cbranch_scc1 .Latt_lat_v_issued
	v_lshl_add_u64 v[4:5], v[4:5], 0, s[8:9]
	global_load_dwordx4 v[142:145], v[4:5], off
.Latt_lat_v_issued:
	s_lshl_b32 s2, s14, 2
	v_readlane_b32 s8, v254, 60
	s_nop 0
	s_or_b32 s16, s2, s8
	s_lshl_b64 s[2:3], s[16:17], 18
	s_lshl_b64 s[14:15], s[2:3], 1
	v_readlane_b32 s16, v255, 2
	s_nop 0
	s_add_u32 s14, s16, s14
	v_readlane_b32 s16, v255, 3
	s_nop 0
	s_addc_u32 s15, s16, s15
	s_lshl_b32 s16, s20, 1
	s_add_u32 s14, s14, s16
	s_addc_u32 s15, s15, 0
	v_lshlrev_b32_e32 v0, 1, v156
	v_ashrrev_i32_e32 v8, 3, v146
	v_lshl_add_u64 v[2:3], s[14:15], 0, v[0:1]
	v_ashrrev_i32_e32 v9, 31, v8
	v_lshlrev_b64 v[4:5], 11, v[8:9]
	s_mov_b64 s[14:15], 0x20000
	v_lshl_add_u64 v[4:5], v[2:3], 0, v[4:5]
	global_load_dwordx4 v[114:117], v[4:5], off
	v_lshl_add_u64 v[4:5], v[4:5], 0, s[14:15]
	global_load_dwordx4 v[118:121], v[4:5], off
	v_lshl_add_u64 v[4:5], v[4:5], 0, s[14:15]
	global_load_dwordx4 v[122:125], v[4:5], off
	v_lshl_add_u64 v[4:5], v[4:5], 0, s[14:15]
	global_load_dwordx4 v[126:129], v[4:5], off
	s_lshr_b32 s16, s19, 3
	s_mov_b64 s[8:9], exec
	v_readlane_b32 s14, v255, 11
	v_readlane_b32 s15, v255, 12
	s_nop 0
	s_and_b64 s[14:15], s[8:9], s[14:15]
	s_mov_b64 exec, s[14:15]
	s_cbranch_execz .LBB0_719
	s_and_b32 s24, s16, 15
	v_readlane_b32 s25, v254, 28
	s_nop 0
	s_add_i32 s24, s25, s24
	v_readlane_b32 s25, v254, 4
	s_nop 1
	v_mov_b32_e32 v0, s25
	ds_read_b64 v[2:3], v0
	v_mov_b32_e32 v0, 0x744
	s_nop 0
	v_mad_u64_u32 v[4:5], s[24:25], s24, v0, v[158:159]
	s_waitcnt lgkmcnt(0)
	v_readfirstlane_b32 s24, v2
	v_readfirstlane_b32 s25, v3
	s_nop 1
	v_lshl_add_u64 v[8:9], s[24:25], 0, v[4:5]
	global_load_dword v130, v[8:9], off
.LBB0_719:
	s_or_b64 exec, exec, s[8:9]
	s_lshl_b64 s[2:3], s[2:3], 1
	v_readlane_b32 s8, v255, 4
	s_add_u32 s2, s8, s2
	v_readlane_b32 s8, v255, 5
	s_addc_u32 s3, s8, s3
	s_lshl_b32 s20, s20, 1
	s_add_u32 s21, s2, s20
	s_mul_i32 s2, s1, 0x7c
	s_addc_u32 s27, s3, 0
	v_add_u32_e32 v0, s2, v171
	s_lshl_b32 s2, s30, 4
	s_and_b32 s2, s2, 0xfffff800
	s_addk_i32 s2, 0x2000
	s_and_b32 s8, s16, 15
	s_mul_hi_u32 s3, s2, 0x7c00
	s_mulk_i32 s2, 0x7c00
	s_lshl_b32 s8, s8, 7
	s_or_b32 s2, s2, s8
	s_mul_i32 s8, s1, 0x1f0000
	s_add_i32 s8, s8, 0xff840000
	s_add_u32 s2, s2, s8
	s_addc_u32 s3, s3, 0
	v_readlane_b32 s8, v255, 9
	s_mulk_i32 s10, 0x1f0
	s_add_u32 s2, s8, s2
	v_readlane_b32 s8, v255, 10
	v_subrev_u32_e32 v173, s10, v0
	s_addc_u32 s3, s8, s3
	v_lshl_add_u32 v0, s1, 13, v147
	s_lshl_b32 s1, s11, 13
	v_mov_b32_e32 v14, v1
	v_mov_b32_e32 v15, v1
	v_subrev_u32_e32 v174, s1, v0
	v_mov_b32_e32 v0, v1
	v_mov_b32_e32 v2, v1
	v_mov_b32_e32 v3, v1
	v_mov_b32_e32 v4, v1
	v_mov_b32_e32 v5, v1
	v_mov_b32_e32 v6, v1
	v_mov_b32_e32 v7, v1
	v_mov_b32_e32 v8, v1
	v_mov_b32_e32 v9, v1
	v_mov_b32_e32 v10, v1
	v_mov_b32_e32 v11, v1
	v_mov_b32_e32 v12, v1
	v_mov_b32_e32 v13, v1
	v_mov_b64_e32 v[64:65], v[14:15]
	v_mov_b64_e32 v[48:49], v[14:15]
	s_mov_b32 s1, 0
	v_mov_b32_e32 v176, 0
	v_mov_b32_e32 v178, 0xff61b1e6
	s_movk_i32 s16, 0xfe40
	v_mov_b32_e32 v175, v147
	v_mov_b64_e32 v[62:63], v[12:13]
	v_mov_b64_e32 v[60:61], v[10:11]
	v_mov_b64_e32 v[58:59], v[8:9]
	v_mov_b64_e32 v[56:57], v[6:7]
	v_mov_b64_e32 v[54:55], v[4:5]
	v_mov_b64_e32 v[52:53], v[2:3]
	v_mov_b64_e32 v[50:51], v[0:1]
	v_mov_b64_e32 v[46:47], v[12:13]
	v_mov_b64_e32 v[44:45], v[10:11]
	v_mov_b64_e32 v[42:43], v[8:9]
	v_mov_b64_e32 v[40:41], v[6:7]
	v_mov_b64_e32 v[38:39], v[4:5]
	v_mov_b64_e32 v[36:37], v[2:3]
	v_mov_b64_e32 v[34:35], v[0:1]
	s_mov_b32 s10, 0xff61b1e6
	s_waitcnt vmcnt(0)
	v_ashrrev_i32_e32 v131, 3, v146
	v_lshl_add_u32 v132, v131, 7, v168
	v_lshl_add_u32 v131, v131, 7, v167
	v_add_u32_e32 v133, 0x10000, v131
	ds_write_b128 v131, v[180:183]
	ds_write_b128 v131, v[184:187] offset:8192
	ds_write_b128 v131, v[188:191] offset:16384
	ds_write_b128 v131, v[192:195] offset:24576
	ds_write_b128 v131, v[196:199] offset:32768
	ds_write_b128 v131, v[200:203] offset:40960
	ds_write_b128 v131, v[204:207] offset:49152
	ds_write_b128 v131, v[208:211] offset:57344
	s_cmpk_lt_u32 s32, 0x1200
	s_cbranch_scc1 .Latt_lat_v_written
	ds_write_b128 v133, v[212:215]
	s_cmpk_lt_u32 s32, 0x1400
	s_cbranch_scc1 .Latt_lat_v_written
	ds_write_b128 v133, v[216:219] offset:8192
	s_cmpk_lt_u32 s32, 0x1600
	s_cbranch_scc1 .Latt_lat_v_written
	ds_write_b128 v133, v[142:145] offset:16384
.Latt_lat_v_written:
	ds_write_b128 v132, v[114:117]
	ds_write_b128 v132, v[118:121] offset:8192
	ds_write_b128 v132, v[122:125] offset:16384
	ds_write_b128 v132, v[126:129] offset:24576
	v_readlane_b32 s14, v255, 11
	v_readlane_b32 s15, v255, 12
	s_mov_b64 s[8:9], exec
	s_nop 0
	s_and_b64 exec, exec, s[14:15]
	v_mul_f32_e32 v130, 0x3fb8aa3b, v130
	ds_write_b32 v170, v130
	s_mov_b64 exec, s[8:9]
	s_waitcnt lgkmcnt(0)
	s_barrier
	s_mov_b64 s[8:9], 0x3e00
	s_cmp_lt_u32 s1, 7
	s_mov_b64 s[14:15], s[2:3]
	s_cbranch_scc0 .LBB0_721
	s_branch .LBB0_722

.LBB0_732:
	s_and_b64 vcc, exec, s[2:3]
	s_cbranch_vccz .LBB0_708
	s_lshl_b32 s1, s19, 4
	s_and_b32 s1, s1, 0xffffff00
	s_waitcnt vmcnt(7)
	v_add_u32_e32 v116, s1, v166
	v_mov_b64_e32 v[2:3], s[4:5]
	v_mad_i64_i32 v[2:3], s[2:3], v116, s29, v[2:3]
	s_lshl_b32 s2, s19, 6
	s_and_b32 s2, s2, 0x3c0
	s_lshl_b32 s16, s2, 1
	s_mul_i32 s3, s1, 0x7c00
	s_mul_hi_i32 s2, s1, 0x7c00
	s_add_u32 s3, s4, s3
	s_addc_u32 s8, s5, s2
	v_lshl_add_u64 v[2:3], v[2:3], 0, s[16:17]
	s_add_u32 s2, s3, s16
	v_lshl_add_u64 v[2:3], v[148:149], 1, v[2:3]
	s_addc_u32 s3, s8, 0
	v_mov_b32_e32 v163, v1
	global_load_dwordx4 v[66:69], v[2:3], off
	global_load_dwordx4 v[70:73], v[2:3], off offset:32
	global_load_dwordx4 v[74:77], v[2:3], off offset:64
	global_load_dwordx4 v[78:81], v[2:3], off offset:96
	v_lshl_add_u64 v[2:3], s[2:3], 0, v[162:163]
	v_lshl_add_u64 v[2:3], v[152:153], 1, v[2:3]
	global_load_dwordx4 v[82:85], v[2:3], off offset:2048
	global_load_dwordx4 v[86:89], v[2:3], off offset:2080
	global_load_dwordx4 v[90:93], v[2:3], off offset:2112
	global_load_dwordx4 v[94:97], v[2:3], off offset:2144
	v_add_co_u32_e32 v2, vcc, 0xf8000, v2
	s_nop 1
	v_addc_co_u32_e32 v3, vcc, 0, v3, vcc
	global_load_dwordx4 v[98:101], v[2:3], off offset:2048
	global_load_dwordx4 v[102:105], v[2:3], off offset:2080
	global_load_dwordx4 v[106:109], v[2:3], off offset:2112
	global_load_dwordx4 v[110:113], v[2:3], off offset:2144
	s_mov_b64 s[2:3], exec
	v_readlane_b32 s8, v255, 6
	v_readlane_b32 s9, v255, 7
	s_and_b64 s[8:9], s[2:3], s[8:9]
	s_movk_i32 s14, 0x5ff
	s_mov_b64 exec, s[8:9]
	s_cbranch_execz .LBB0_736
	v_ashrrev_i32_e32 v3, 3, v146
	v_mov_b64_e32 v[4:5], s[4:5]
	v_add_u32_e32 v6, s1, v3
	v_mad_i64_i32 v[4:5], s[10:11], v6, s29, v[4:5]
	v_lshlrev_b32_e32 v0, 1, v156
	v_lshl_add_u64 v[4:5], v[4:5], 0, s[16:17]
	v_lshl_add_u64 v[4:5], v[4:5], 0, v[0:1]
	v_add_co_u32_e32 v4, vcc, 0x1000, v4
	s_mov_b64 s[8:9], 0x1f0000
	s_nop 0
	v_addc_co_u32_e32 v5, vcc, 0, v5, vcc
	global_load_dwordx4 v[180:183], v[4:5], off
	v_lshl_add_u64 v[4:5], v[4:5], 0, s[8:9]
	global_load_dwordx4 v[184:187], v[4:5], off
	v_lshl_add_u64 v[4:5], v[4:5], 0, s[8:9]
	global_load_dwordx4 v[188:191], v[4:5], off
	v_lshl_add_u64 v[4:5], v[4:5], 0, s[8:9]
	global_load_dwordx4 v[192:195], v[4:5], off
	v_lshl_add_u32 v3, v3, 7, v167
	s_waitcnt vmcnt(0)
	ds_write_b128 v3, v[180:183]
	ds_write_b128 v3, v[184:187] offset:8192
	ds_write_b128 v3, v[188:191] offset:16384
	ds_write_b128 v3, v[192:195] offset:24576
